# attention item: chunk-0 K and V^T loads issued at the item start behind the Q tile loads
# speedup vs baseline: 1.1533x; 1.0004x over previous
.LBB0_189:
	v_cndmask_b32_e64 v0, 0, 1, s[0:1]
	v_readlane_b32 s4, v252, 57
	s_andn2_b64 vcc, exec, s[0:1]
	s_and_b32 s18, s3, 7
	s_lshl_b32 s100, s18, 7
	s_add_u32 s100, s92, s100
	s_addc_u32 s101, s93, 0
	v_lshlrev_b32_e32 v100, 3, v175
	v_and_b32_e32 v100, 56, v100
	v_lshlrev_b32_e32 v100, 1, v100
	v_ashrrev_i32_e32 v101, 3, v175
	v_add_u32_e32 v101, s11, v101
	v_mul_u32_u24_e32 v101, 0x1200, v101
	v_add_u32_e32 v101, v101, v100
	global_load_dwordx4 v[104:107], v101, s[100:101]
	v_add_u32_e32 v101, 0x24000, v101
	global_load_dwordx4 v[108:111], v101, s[100:101]
	v_add_u32_e32 v101, 0x24000, v101
	global_load_dwordx4 v[112:115], v101, s[100:101]
	v_add_u32_e32 v101, 0x24000, v101
	global_load_dwordx4 v[116:119], v101, s[100:101]
	v_add_u32_e32 v101, 0x24000, v101
	global_load_dwordx4 v[120:123], v101, s[100:101]
	v_add_u32_e32 v101, 0x24000, v101
	global_load_dwordx4 v[124:127], v101, s[100:101]
	v_add_u32_e32 v101, 0x24000, v101
	global_load_dwordx4 v[128:131], v101, s[100:101]
	v_add_u32_e32 v101, 0x24000, v101
	global_load_dwordx4 v[132:135], v101, s[100:101]
	s_lshl_b32 s100, s15, 11
	s_lshl_b32 s101, s14, 6
	s_or_b32 s100, s100, s101
	s_lshl_b32 s101, s15, 8
	s_addk_i32 s101, 0x4000
	s_lshl_b32 s26, s13, 6
	s_sub_i32 s101, s101, s26
	s_cmp_lt_i32 s13, 1
	s_cselect_b32 s100, s101, s100
	v_ashrrev_i32_e32 v101, 3, v175
	v_add_u32_e32 v101, s100, v101
	v_mul_u32_u24_e32 v101, 0x1200, v101
	v_add_u32_e32 v101, v101, v100
	s_lshl_b32 s101, s18, 7
	v_add_u32_e32 v101, s101, v101
	global_load_dwordx4 v[54:57], v101, s[92:93] offset:1024
	v_add_u32_e32 v101, 0x24000, v101
	global_load_dwordx4 v[58:61], v101, s[92:93] offset:1024
	v_ashrrev_i32_e32 v101, 2, v175
	s_lshl_b32 s101, s18, 6
	v_add_u32_e32 v101, s101, v101
	v_mul_u32_u24_e32 v101, 0x9000, v101
	s_lshl_b32 s101, s100, 1
	v_add_u32_e32 v101, s101, v101
	v_lshlrev_b32_e32 v102, 1, v175
	v_and_b32_e32 v102, 6, v102
	v_lshl_add_u32 v101, v102, 4, v101
	v_readlane_b32 s100, v250, 10
	v_readlane_b32 s101, v250, 11
	s_nop 4
	global_load_dwordx4 v[62:65], v101, s[100:101] offset:16
	global_load_dwordx4 v[66:69], v101, s[100:101]
	v_or_b32_e32 v4, s4, v0
	v_ashrrev_i32_e32 v5, 31, v4
	v_lshlrev_b64 v[4:5], 2, v[4:5]
	v_lshl_add_u64 v[4:5], s[94:95], 0, v[4:5]
	global_load_dword v74, v[4:5], off
	s_cbranch_vccnz .LBB0_199
	s_movk_i32 s0, 0x1d1
	v_cmp_gt_i32_e32 vcc, s0, v2
	s_and_saveexec_b64 s[0:1], vcc
	s_cbranch_execz .LBB0_198
	v_max_i32_e32 v0, 0xd1, v2
	v_sub_u32_e32 v0, v0, v2
	v_add_u32_e32 v0, 0xff, v0
	v_cmp_lt_u32_e32 vcc, s33, v0
	s_mov_b64 s[6:7], -1
	v_mov_b32_e32 v4, v2
	s_and_saveexec_b64 s[4:5], vcc
	s_cbranch_execz .LBB0_195
	v_readlane_b32 s6, v252, 58
	v_readlane_b32 s7, v252, 59
	s_or_b32 s3, s6, s18
	v_lshrrev_b32_e32 v0, 8, v0
	s_mul_i32 s6, s7, 0x744
	s_mul_hi_u32 s7, s3, 0x744
	v_readlane_b32 s56, v251, 46
	v_add_u32_e32 v0, 1, v0
	s_add_i32 s7, s7, s6
	s_mulk_i32 s3, 0x744
	v_readlane_b32 s62, v251, 52
	v_readlane_b32 s63, v251, 53
	s_add_u32 s6, s62, s3
	v_and_b32_e32 v6, 0x1fffffe, v0
	v_add_u32_e32 v3, 0x100, v2
	v_readlane_b32 s3, v252, 0
	s_addc_u32 s7, s63, s7
	s_waitcnt vmcnt(0)
	v_mov_b32_e32 v75, v74
	v_lshl_add_u32 v7, v2, 2, s3
	s_mov_b64 s[8:9], 0
	v_mov_b32_e32 v8, v6
	v_mov_b64_e32 v[4:5], v[2:3]
	v_readlane_b32 s57, v251, 47
	v_readlane_b32 s58, v251, 48
	v_readlane_b32 s59, v251, 49
	v_readlane_b32 s60, v251, 50
	v_readlane_b32 s61, v251, 51
	v_readlane_b32 s64, v251, 54
	v_readlane_b32 s65, v251, 55
	v_readlane_b32 s66, v251, 56
	v_readlane_b32 s67, v251, 57
	v_readlane_b32 s68, v251, 58
	v_readlane_b32 s69, v251, 59
	v_readlane_b32 s70, v251, 60
	v_readlane_b32 s71, v251, 61

.LBB0_202:
	v_and_b32_e32 v5, 64, v207
	v_add_u32_e32 v180, 64, v5
	v_ashrrev_i32_e32 v4, 3, v175
	v_lshrrev_b32_e32 v32, 1, v4
	v_bitop3_b32 v0, v32, 7, v175 bitop3:0x48
	v_lshlrev_b32_e32 v0, 4, v0
	v_lshl_or_b32 v0, v4, 7, v0
	v_add_u32_e32 v3, s18, v0
	s_waitcnt vmcnt(0)
	ds_write_b128 v3, v[104:107]
	ds_write_b128 v3, v[108:111] offset:4096
	ds_write_b128 v3, v[112:115] offset:8192
	ds_write_b128 v3, v[116:119] offset:12288
	ds_write_b128 v3, v[120:123] offset:16384
	ds_write_b128 v3, v[124:127] offset:20480
	ds_write_b128 v3, v[128:131] offset:24576
	ds_write_b128 v3, v[132:135] offset:28672
	s_cmp_lt_i32 s13, 1
	s_mov_b64 s[6:7], -1
	s_waitcnt lgkmcnt(0)
	s_barrier
	s_cbranch_scc0 .LBB0_205
	s_lshl_b32 s0, s15, 8
	s_lshl_b32 s1, s13, 6
	s_sub_i32 s0, s0, s1
	s_addk_i32 s0, 0x4000
	s_mov_b64 s[6:7], 0

.LBB0_207:
	v_ashrrev_i32_e32 v184, 3, v2
	v_add_u32_e32 v3, s0, v184
	v_mov_b64_e32 v[4:5], s[92:93]
	v_mad_i64_i32 v[6:7], s[6:7], v3, s28, v[4:5]
	v_lshlrev_b32_e32 v0, 3, v2
	v_add_u32_e32 v3, 32, v3
	s_lshl_b32 s26, s3, 1
	v_and_b32_e32 v44, 56, v0
	v_mad_i64_i32 v[4:5], s[6:7], v3, s28, v[4:5]
	v_lshl_add_u64 v[6:7], v[6:7], 0, s[26:27]
	v_lshlrev_b32_e32 v0, 1, v44
	v_lshl_add_u64 v[4:5], v[4:5], 0, s[26:27]
	v_lshl_add_u64 v[6:7], v[6:7], 0, v[0:1]
	v_lshl_add_u64 v[4:5], v[4:5], 0, v[0:1]
	v_readlane_b32 s6, v250, 10
	v_ashrrev_i32_e32 v45, 2, v2
	v_readlane_b32 s7, v250, 11
	v_lshlrev_b32_e32 v3, 1, v2
	v_add_u32_e32 v6, s3, v45
	v_mov_b64_e32 v[4:5], s[6:7]
	s_ashr_i32 s1, s0, 31
	v_and_b32_e32 v75, 6, v3
	v_mad_i64_i32 v[166:167], s[6:7], v6, s19, v[4:5]
	v_mov_b32_e32 v7, v1
	v_lshlrev_b32_e32 v6, 4, v75
	v_lshl_add_u64 v[4:5], s[0:1], 1, v[166:167]
	v_lshl_add_u64 v[4:5], v[4:5], 0, v[6:7]
	v_lshrrev_b32_e32 v3, 1, v184
	v_and_b32_e32 v179, 15, v2
	v_bfe_u32 v178, v2, 4, 2
	v_xor_b32_e32 v2, v3, v2
	v_lshl_add_u32 v185, v44, 2, 0
	v_mov_b32_e32 v165, 0
	s_cmp_lt_i32 s13, -3
	v_mov_b32_e32 v164, 0
	v_mov_b32_e32 v163, 0
	v_mov_b32_e32 v162, 0
	v_mov_b32_e32 v85, 0
	v_mov_b32_e32 v84, v165
	v_mov_b32_e32 v83, v165
	v_mov_b32_e32 v82, v165
	v_mov_b32_e32 v81, 0
	v_mov_b32_e32 v80, v165
	v_mov_b32_e32 v79, v165
	v_mov_b32_e32 v78, v165
	v_mov_b32_e32 v73, 0
	v_mov_b32_e32 v72, v165
	v_mov_b32_e32 v71, v165
	v_mov_b32_e32 v70, v165
	v_mov_b32_e32 v53, 0
	v_mov_b32_e32 v52, v165
	v_mov_b32_e32 v51, v165
	v_mov_b32_e32 v50, v165
	v_mov_b32_e32 v49, 0
	v_mov_b32_e32 v48, v165
	v_mov_b32_e32 v47, v165
	v_mov_b32_e32 v46, v165
	v_mov_b32_e32 v44, v165
	v_lshlrev_b32_e32 v32, 3, v2
	v_lshlrev_b32_e32 v30, 6, v184
	v_and_or_b32 v186, v32, 56, v30
	v_or_b32_e32 v31, 1, v75
	v_mov_b32_e32 v43, v165
	v_mov_b32_e32 v42, v165
	v_mov_b32_e32 v41, 0
	v_mov_b32_e32 v40, v165
	v_mov_b32_e32 v39, v165
	v_mov_b32_e32 v38, v165
	v_mov_b32_e32 v37, 0
	v_mov_b32_e32 v36, v165
	v_mov_b32_e32 v35, v165
	v_mov_b32_e32 v34, v165
	v_lshl_add_u32 v29, v186, 1, 0
	s_waitcnt vmcnt(3)
	ds_write_b128 v29, v[54:57]
	s_waitcnt vmcnt(2)
	ds_write_b128 v29, v[58:61] offset:4096
	v_mov_b32_e32 v33, 0
	v_lshrrev_b32_e32 v3, 1, v45
	v_lshlrev_b32_e32 v2, 6, v45
	v_bitop3_b32 v4, v3, v75, 7 bitop3:0x6c
	v_bitop3_b32 v3, v3, v31, 7 bitop3:0x6c
	v_lshl_or_b32 v187, v4, 3, v2
	v_lshl_or_b32 v188, v3, 3, v2
	v_lshl_add_u32 v4, v187, 1, 0
	v_lshl_add_u32 v2, v188, 1, 0
	s_waitcnt vmcnt(0)
	ds_write_b128 v4, v[66:69] offset:16384
	ds_write_b128 v2, v[62:65] offset:16384
	v_mov_b32_e32 v45, 0
	v_mov_b32_e32 v32, v165
	v_mov_b32_e32 v31, v165
	v_mov_b32_e32 v30, v165
	v_mov_b32_e32 v29, 0
	v_mov_b32_e32 v28, v165
	v_mov_b32_e32 v27, v165
	v_mov_b32_e32 v26, v165
	v_mov_b32_e32 v25, 0
	v_mov_b32_e32 v24, v165
	v_mov_b32_e32 v23, v165
	v_mov_b32_e32 v22, v165
	v_mov_b32_e32 v21, 0
	v_mov_b32_e32 v20, v165
	v_mov_b32_e32 v19, v165
	v_mov_b32_e32 v18, v165
	v_mov_b32_e32 v17, 0
	v_mov_b32_e32 v16, v165
	v_mov_b32_e32 v15, v165
	v_mov_b32_e32 v14, v165
	v_mov_b32_e32 v13, 0
	v_mov_b32_e32 v12, v165
	v_mov_b32_e32 v11, v165
	v_mov_b32_e32 v10, v165
	v_mov_b32_e32 v9, 0
	v_mov_b32_e32 v8, v165
	v_mov_b32_e32 v7, v165
	v_mov_b32_e32 v6, v165
	v_mov_b32_e32 v5, 0
	v_mov_b32_e32 v4, v165
	v_mov_b32_e32 v3, v165
	v_mov_b32_e32 v2, v165
	s_waitcnt lgkmcnt(0)
	s_barrier
	s_cbranch_scc1 .LBB0_225
	s_lshl_b32 s1, s16, 13
	s_add_i32 s16, s1, 0
	v_lshl_add_u64 v[168:169], s[4:5], 0, v[0:1]
	s_mul_i32 s1, s14, 0x7c
	s_mul_i32 s4, s17, 0x7c
	s_sub_i32 s1, s1, s4
	s_add_i32 s1, s1, 0
	s_lshl_b32 s0, s15, 8
	s_add_i32 s17, s1, 0xa360
	s_lshl_b32 s1, s13, 6
	v_lshlrev_b32_e32 v3, 3, v75
	v_xor_b32_e32 v74, 0x80000000, v74
	s_sub_i32 s0, s0, s1
	v_mov_b32_e32 v162, v1
	v_mov_b32_e32 v163, v1
	v_mov_b32_e32 v2, 0
	s_add_i32 s8, s13, 4
	s_lshl_b32 s9, s15, 11
	s_add_i32 s15, s12, 7
	v_mov_b32_e32 v75, v74
	v_mov_b32_e32 v76, v74
	v_mov_b32_e32 v77, v74
	s_add_i32 s18, s0, 0x4040
	s_mov_b32 s19, 0
	v_lshlrev_b32_e32 v0, 1, v3
	s_mov_b32 s21, 0
	v_mov_b64_e32 v[164:165], v[162:163]
	v_mov_b32_e32 v3, v2
	v_mov_b32_e32 v4, v2
	v_mov_b32_e32 v5, v2
	v_mov_b32_e32 v6, v2
	v_mov_b32_e32 v7, v2
	v_mov_b32_e32 v8, v2
	v_mov_b32_e32 v9, v2
	v_mov_b32_e32 v10, v2
	v_mov_b32_e32 v11, v2
	v_mov_b32_e32 v12, v2
	v_mov_b32_e32 v13, v2
	v_mov_b32_e32 v14, v2
	v_mov_b32_e32 v15, v2
	v_mov_b32_e32 v16, v2
	v_mov_b32_e32 v17, v2
	v_mov_b32_e32 v18, v2
	v_mov_b32_e32 v19, v2
	v_mov_b32_e32 v20, v2
	v_mov_b32_e32 v21, v2
	v_mov_b32_e32 v22, v2
	v_mov_b32_e32 v23, v2
	v_mov_b32_e32 v24, v2
	v_mov_b32_e32 v25, v2
	v_mov_b32_e32 v26, v2
	v_mov_b32_e32 v27, v2
	v_mov_b32_e32 v28, v2
	v_mov_b32_e32 v29, v2
	v_mov_b32_e32 v30, v2
	v_mov_b32_e32 v31, v2
	v_mov_b32_e32 v32, v2
	v_mov_b32_e32 v33, v2
	v_mov_b32_e32 v34, v2
	v_mov_b32_e32 v35, v2
	v_mov_b32_e32 v36, v2
	v_mov_b32_e32 v37, v2
	v_mov_b32_e32 v38, v2
	v_mov_b32_e32 v39, v2
	v_mov_b32_e32 v40, v2
	v_mov_b32_e32 v41, v2
	v_mov_b32_e32 v42, v2
	v_mov_b32_e32 v43, v2
	v_mov_b32_e32 v44, v2
	v_mov_b32_e32 v45, v2
	v_mov_b32_e32 v46, v2
	v_mov_b32_e32 v47, v2
	v_mov_b32_e32 v48, v2
	v_mov_b32_e32 v49, v2
	v_mov_b32_e32 v50, v2
	v_mov_b32_e32 v51, v2
	v_mov_b32_e32 v52, v2
	v_mov_b32_e32 v53, v2
	v_mov_b32_e32 v70, v2
	v_mov_b32_e32 v71, v2
	v_mov_b32_e32 v72, v2
	v_mov_b32_e32 v73, v2
	v_mov_b32_e32 v78, v2
	v_mov_b32_e32 v79, v2
	v_mov_b32_e32 v80, v2
	v_mov_b32_e32 v81, v2
	v_mov_b32_e32 v82, v2
	v_mov_b32_e32 v83, v2
	v_mov_b32_e32 v84, v2
	v_mov_b32_e32 v85, v2
